# attention row-max: the two dependent ds_bpermute steps (xor 16, xor 32) replaced by three independent bpermutes (xor 16/32/48) behind one wait
# baseline (speedup 1.0000x reference)
; #define LAS __attribute__((address_space(3)))
; template <bool SWA>
; DI void attn_phase(const Ctx& a, LAS unsigned char* lds) {
;     ...
;             if (nck == 2) {
;                 const int tkey0 = rlo + 64 * tl;
;                 f32x4 sc[4];
; #pragma unroll
;                 for (int jt = 0; jt < 4; ++jt) {
;                     const int row = 16 * jt + fr; const int sw = (row >> 1) & 7;
;                     const bf16x8 k0 = *(const LAS bf16x8*)(lds + AT_K + buf * 8192 + row * 128 + ((fq ^ sw) << 4));
;                     const bf16x8 k1 = *(const LAS bf16x8*)(lds + AT_K + buf * 8192 + row * 128 + (((4 + fq) ^ sw) << 4));
;                     f32x4 acc = (f32x4){0.f, 0.f, 0.f, 0.f}; acc = MFMA16(k0, qf[0], acc); acc = MFMA16(k1, qf[1], acc); sc[jt] = acc;
;                 }
;                 float sv[16]; bool ok[16];
; #pragma unroll
;                 for (int jt = 0; jt < 4; ++jt)
; #pragma unroll
;                     for (int rr = 0; rr < 4; ++rr) {
;                         bool valid = true;
;                         if (SWA && local) { const int dd = tkey0 + 16 * jt + 4 * fq + rr - (tq0 + fr); valid = (dd <= 128) && (dd >= -128); }
;                         sv[jt * 4 + rr] = valid ? sc[jt][rr] : -1e30f; ok[jt * 4 + rr] = valid;
;                     }
;                 float cmax = sv[0];
; #pragma unroll
;                 for (int e = 1; e < 16; ++e) cmax = fmaxf(cmax, sv[e]);
;                 cmax = fmaxf(cmax, shx(cmax, 16, lane)); cmax = fmaxf(cmax, shx(cmax, 32, lane));
;                 const float m_new = fmaxf(m_run, cmax);
;                 const float alpha = __builtin_amdgcn_exp2f((m_run - m_new) * LOG2E);
;                 float p[16], psum = 0.f;
; #pragma unroll
;                 for (int e = 0; e < 16; ++e) { p[e] = ok[e] ? __builtin_amdgcn_exp2f((sv[e] - m_new) * LOG2E) : 0.f; psum += p[e]; }
;                 l_run = l_run * alpha + psum; m_run = m_new;
;                 u32x4 pw0, pw1; pw0.x = pk2(p[0], p[1]); pw0.y = pk2(p[2], p[3]); pw0.z = pk2(p[4], p[5]); pw0.w = pk2(p[6], p[7]);
;                 pw1.x = pk2(p[8], p[9]); pw1.y = pk2(p[10], p[11]); pw1.z = pk2(p[12], p[13]); pw1.w = pk2(p[14], p[15]);
;                 const bf16x8 pf0 = __builtin_bit_cast(bf16x8, pw0), pf1 = __builtin_bit_cast(bf16x8, pw1);
;                 if (__builtin_amdgcn_ballot_w64(alpha != 1.f) != 0ull) {
; #pragma unroll
.LBB0_78:
	v_add_u32_e32 v79, v65, v66
	v_add_u32_e32 v80, v65, v67
	ds_read_b128 v[0:3], v79
	ds_read_b128 v[4:7], v79 offset:2048
	ds_read_b128 v[8:11], v80
	ds_read_b128 v[20:23], v80 offset:2048
	s_waitcnt lgkmcnt(0)
	v_mfma_f32_16x16x32_bf16 v[0:3], v[0:3], v[12:15], 0
	v_add_u32_e32 v77, v74, v70
	v_add_u32_e32 v78, v74, v71
	v_add_u32_e32 v76, v74, v73
	v_mfma_f32_16x16x32_bf16 v[0:3], v[8:11], v[16:19], v[0:3]
	ds_read_b128 v[8:11], v79 offset:4096
	v_mfma_f32_16x16x32_bf16 v[4:7], v[4:7], v[12:15], 0
	s_nop 5
	v_max_f32_e32 v34, v1, v1
	v_max_f32_e32 v35, v0, v0
	v_mfma_f32_16x16x32_bf16 v[4:7], v[20:23], v[16:19], v[4:7]
	ds_read_b128 v[20:23], v80 offset:4096
	ds_read_b128 v[26:29], v79 offset:6144
	ds_read_b128 v[30:33], v80 offset:6144
	ds_read_b64 v[122:123], v76 offset:24576
	ds_read_b64 v[130:131], v76 offset:26624
	s_waitcnt lgkmcnt(0)
	v_mfma_f32_16x16x32_bf16 v[8:11], v[8:11], v[12:15], 0
	v_mfma_f32_16x16x32_bf16 v[8:11], v[20:23], v[16:19], v[8:11]
	v_max_f32_e32 v20, v35, v34
	v_max3_f32 v20, v20, v2, v3
	v_max3_f32 v34, v20, v4, v5
	v_mfma_f32_16x16x32_bf16 v[20:23], v[26:29], v[12:15], 0
	v_max3_f32 v26, v34, v6, v7
	s_nop 2
	v_max3_f32 v26, v26, v8, v9
	v_max3_f32 v26, v26, v10, v11
	v_mfma_f32_16x16x32_bf16 v[20:23], v[30:33], v[16:19], v[20:23]
	s_nop 6
	s_nop 0
	v_max3_f32 v26, v26, v20, v21
	v_max3_f32 v26, v26, v22, v23
	v_xor_b32_e32 v157, 64, v69
	ds_bpermute_b32 v27, v68, v26
	ds_bpermute_b32 v158, v69, v26
	ds_bpermute_b32 v159, v157, v26
	s_waitcnt lgkmcnt(0)
	v_max3_f32 v26, v26, v27, v158
	v_max3_f32 v60, v25, v26, v159
	v_sub_f32_e32 v0, v0, v60
	v_sub_f32_e32 v25, v25, v60
	v_mul_f32_e32 v0, 0x3fb8aa3b, v0
	v_mul_f32_e32 v49, 0x3fb8aa3b, v25
	v_exp_f32_e32 v25, v0
	v_sub_f32_e32 v0, v3, v60
	v_mul_f32_e32 v0, 0x3fb8aa3b, v0
	v_exp_f32_e32 v28, v0
	v_sub_f32_e32 v0, v4, v60
	v_mul_f32_e32 v0, 0x3fb8aa3b, v0
	v_exp_f32_e32 v29, v0
	v_sub_f32_e32 v0, v5, v60
	v_mul_f32_e32 v0, 0x3fb8aa3b, v0
	v_exp_f32_e32 v30, v0
	v_sub_f32_e32 v0, v6, v60
	v_mul_f32_e32 v0, 0x3fb8aa3b, v0
	v_exp_f32_e32 v31, v0
	v_sub_f32_e32 v0, v7, v60
	v_mul_f32_e32 v0, 0x3fb8aa3b, v0
	v_exp_f32_e32 v32, v0
	v_sub_f32_e32 v0, v8, v60
	v_mul_f32_e32 v0, 0x3fb8aa3b, v0
	v_exp_f32_e32 v33, v0
	v_sub_f32_e32 v0, v9, v60
	v_exp_f32_e32 v84, v49
	v_mul_f32_e32 v0, 0x3fb8aa3b, v0
	v_exp_f32_e32 v34, v0
	v_sub_f32_e32 v0, v10, v60
	v_mul_f32_e32 v0, 0x3fb8aa3b, v0
	v_exp_f32_e32 v35, v0
	v_sub_f32_e32 v0, v11, v60
	v_cmp_neq_f32_e32 vcc, 1.0, v84
	v_mul_f32_e32 v0, 0x3fb8aa3b, v0
	s_cmp_lg_u64 vcc, 0
	v_exp_f32_e32 v36, v0
	v_sub_f32_e32 v0, v20, v60
	v_mul_f32_e32 v4, 0, v84
	s_cselect_b64 vcc, -1, 0
	v_mul_f32_e32 v0, 0x3fb8aa3b, v0
	v_cndmask_b32_e32 v90, 0, v4, vcc
	ds_read_b64 v[116:117], v77 offset:24576
	ds_read_b64 v[124:125], v77 offset:26624
	ds_read_b64 v[118:119], v78 offset:24576
	ds_read_b64 v[126:127], v78 offset:26624
	v_exp_f32_e32 v37, v0
	v_sub_f32_e32 v0, v21, v60
	v_mul_f32_e32 v0, 0x3fb8aa3b, v0
	v_sub_f32_e32 v1, v1, v60
	v_sub_f32_e32 v2, v2, v60
	v_exp_f32_e32 v38, v0
	v_sub_f32_e32 v0, v22, v60
	v_add_u32_e32 v49, v74, v72
	v_mul_f32_e32 v1, 0x3fb8aa3b, v1
	v_mul_f32_e32 v2, 0x3fb8aa3b, v2
	v_mul_f32_e32 v0, 0x3fb8aa3b, v0
	ds_read_b64 v[120:121], v49 offset:24576
	ds_read_b64 v[128:129], v49 offset:26624
	v_exp_f32_e32 v26, v1
	v_exp_f32_e32 v27, v2
	v_exp_f32_e32 v39, v0
	v_sub_f32_e32 v0, v23, v60
	s_waitcnt lgkmcnt(0)
	v_mul_f32_e32 v0, 0x3fb8aa3b, v0
	v_exp_f32_e32 v83, v0
	v_cvt_pk_bf16_f32 v0, v25, v26
	v_cvt_pk_bf16_f32 v1, v27, v28
	v_cvt_pk_bf16_f32 v2, v29, v30
	v_cvt_pk_bf16_f32 v3, v31, v32
	v_mov_b32_e32 v91, v90
	v_mov_b32_e32 v92, v90
	v_mov_b32_e32 v93, v90
	s_nop 1
	v_mfma_f32_16x16x32_bf16 v[20:23], v[116:119], v[0:3], v[90:93]
	v_cvt_pk_bf16_f32 v86, v33, v34
	v_cvt_pk_bf16_f32 v87, v35, v36
	v_cvt_pk_bf16_f32 v88, v37, v38
	v_cvt_pk_bf16_f32 v89, v39, v83
	s_nop 1
	v_mfma_f32_16x16x32_bf16 v[20:23], v[120:123], v[86:89], v[20:23]
	ds_read_b64 v[132:133], v77 offset:28672
	ds_read_b64 v[136:137], v77 offset:30720
	ds_read_b64 v[134:135], v78 offset:28672
	ds_read_b64 v[138:139], v78 offset:30720
	s_andn2_b64 vcc, exec, s[30:31]
	s_mov_b64 s[30:31], -1
	v_mfma_f32_16x16x32_bf16 v[4:7], v[124:127], v[0:3], v[90:93]
	v_mfma_f32_16x16x32_bf16 v[8:11], v[128:131], v[86:89], v[4:7]
	ds_read_b64 v[140:141], v49 offset:28672
	ds_read_b64 v[160:161], v49 offset:30720
	ds_read_b64 v[142:143], v76 offset:28672
	ds_read_b64 v[162:163], v76 offset:30720
	s_waitcnt lgkmcnt(0)
	s_nop 2
	v_mfma_f32_16x16x32_bf16 v[4:7], v[132:135], v[0:3], v[90:93]
	v_mfma_f32_16x16x32_bf16 v[0:3], v[136:139], v[0:3], v[90:93]
	v_mfma_f32_16x16x32_bf16 v[4:7], v[140:143], v[86:89], v[4:7]
	v_mfma_f32_16x16x32_bf16 v[0:3], v[160:163], v[86:89], v[0:3]
	s_cbranch_vccnz .LBB0_80
	s_waitcnt vmcnt(0)
	s_mov_b64 s[30:31], 0

; #define LAS __attribute__((address_space(3)))
; template <bool SWA>
; DI void attn_phase(const Ctx& a, LAS unsigned char* lds) {
;     ...
;             if (nck == 2) {
;                 const int tkey0 = rlo + 64 * tl;
;                 f32x4 sc[4];
; #pragma unroll
;                 for (int jt = 0; jt < 4; ++jt) {
;                     const int row = 16 * jt + fr; const int sw = (row >> 1) & 7;
;                     const bf16x8 k0 = *(const LAS bf16x8*)(lds + AT_K + buf * 8192 + row * 128 + ((fq ^ sw) << 4));
;                     const bf16x8 k1 = *(const LAS bf16x8*)(lds + AT_K + buf * 8192 + row * 128 + (((4 + fq) ^ sw) << 4));
;                     f32x4 acc = (f32x4){0.f, 0.f, 0.f, 0.f}; acc = MFMA16(k0, qf[0], acc); acc = MFMA16(k1, qf[1], acc); sc[jt] = acc;
;                 }
;                 float sv[16]; bool ok[16];
; #pragma unroll
;                 for (int jt = 0; jt < 4; ++jt)
; #pragma unroll
;                     for (int rr = 0; rr < 4; ++rr) {
;                         bool valid = true;
;                         if (SWA && local) { const int dd = tkey0 + 16 * jt + 4 * fq + rr - (tq0 + fr); valid = (dd <= 128) && (dd >= -128); }
;                         sv[jt * 4 + rr] = valid ? sc[jt][rr] : -1e30f; ok[jt * 4 + rr] = valid;
;                     }
;                 float cmax = sv[0];
; #pragma unroll
;                 for (int e = 1; e < 16; ++e) cmax = fmaxf(cmax, sv[e]);
;                 cmax = fmaxf(cmax, shx(cmax, 16, lane)); cmax = fmaxf(cmax, shx(cmax, 32, lane));
;                 const float m_new = fmaxf(m_run, cmax);
;                 const float alpha = __builtin_amdgcn_exp2f((m_run - m_new) * LOG2E);
;                 float p[16], psum = 0.f;
; #pragma unroll
;                 for (int e = 0; e < 16; ++e) { p[e] = ok[e] ? __builtin_amdgcn_exp2f((sv[e] - m_new) * LOG2E) : 0.f; psum += p[e]; }
;                 l_run = l_run * alpha + psum; m_run = m_new;
;                 u32x4 pw0, pw1; pw0.x = pk2(p[0], p[1]); pw0.y = pk2(p[2], p[3]); pw0.z = pk2(p[4], p[5]); pw0.w = pk2(p[6], p[7]);
;                 pw1.x = pk2(p[8], p[9]); pw1.y = pk2(p[10], p[11]); pw1.z = pk2(p[12], p[13]); pw1.w = pk2(p[14], p[15]);
;                 const bf16x8 pf0 = __builtin_bit_cast(bf16x8, pw0), pf1 = __builtin_bit_cast(bf16x8, pw1);
;                 if (__builtin_amdgcn_ballot_w64(alpha != 1.f) != 0ull) {
; #pragma unroll
.LBB0_85:
	ds_read_b128 v[164:167], v79 offset:8192
	ds_read_b128 v[168:171], v80 offset:8192
	ds_read_b128 v[172:175], v79 offset:10240
	ds_read_b128 v[176:179], v80 offset:10240
	ds_read_b128 v[180:183], v79 offset:12288
	ds_read_b128 v[184:187], v80 offset:12288
	ds_read_b128 v[192:195], v79 offset:14336
	ds_read_b128 v[196:199], v80 offset:14336
	s_waitcnt lgkmcnt(6)
	v_mfma_f32_16x16x32_bf16 v[24:27], v[164:167], v[12:15], 0
	v_mfma_f32_16x16x32_bf16 v[24:27], v[168:171], v[16:19], v[24:27]
	s_waitcnt lgkmcnt(4)
	v_mfma_f32_16x16x32_bf16 v[28:31], v[172:175], v[12:15], 0
	v_mfma_f32_16x16x32_bf16 v[28:31], v[176:179], v[16:19], v[28:31]
	s_waitcnt lgkmcnt(2)
	v_mfma_f32_16x16x32_bf16 v[32:35], v[180:183], v[12:15], 0
	v_mfma_f32_16x16x32_bf16 v[32:35], v[184:187], v[16:19], v[32:35]
	s_waitcnt lgkmcnt(0)
	v_mfma_f32_16x16x32_bf16 v[36:39], v[192:195], v[12:15], 0
	v_mfma_f32_16x16x32_bf16 v[36:39], v[196:199], v[16:19], v[36:39]
	v_max_f32_e32 v84, v25, v25
	v_max_f32_e32 v85, v24, v24
	v_max_f32_e32 v84, v85, v84
	v_max3_f32 v84, v84, v26, v27
	v_max3_f32 v84, v84, v28, v29
	v_max3_f32 v84, v84, v30, v31
	v_max3_f32 v84, v84, v32, v33
	v_max3_f32 v84, v84, v34, v35
	v_max3_f32 v84, v84, v36, v37
	v_max3_f32 v84, v84, v38, v39
	v_xor_b32_e32 v157, 64, v69
	ds_bpermute_b32 v85, v68, v84
	ds_bpermute_b32 v158, v69, v84
	ds_bpermute_b32 v159, v157, v84
	s_waitcnt lgkmcnt(0)
	v_max3_f32 v84, v84, v85, v158
	v_max3_f32 v85, v60, v84, v159
	v_sub_f32_e32 v60, v60, v85
	v_mul_f32_e32 v60, 0x3fb8aa3b, v60
	v_exp_f32_e32 v60, v60
	s_nop 0
	v_cmp_neq_f32_e32 vcc, 1.0, v60
	s_cbranch_vccz .LBB0_87
	v_pk_mul_f32 v[22:23], v[22:23], v[60:61] op_sel_hi:[1,0]
	v_pk_mul_f32 v[20:21], v[20:21], v[60:61] op_sel_hi:[1,0]
	v_pk_mul_f32 v[10:11], v[10:11], v[60:61] op_sel_hi:[1,0]
	v_pk_mul_f32 v[8:9], v[8:9], v[60:61] op_sel_hi:[1,0]
	v_pk_mul_f32 v[6:7], v[6:7], v[60:61] op_sel_hi:[1,0]
	v_pk_mul_f32 v[4:5], v[4:5], v[60:61] op_sel_hi:[1,0]
	v_pk_mul_f32 v[2:3], v[2:3], v[60:61] op_sel_hi:[1,0]
	v_pk_mul_f32 v[0:1], v[0:1], v[60:61] op_sel_hi:[1,0]

; #define LAS __attribute__((address_space(3)))
; template <bool SWA>
; DI void attn_phase(const Ctx& a, LAS unsigned char* lds) {
;     ...
;             if (nck == 2) {
;                 const int tkey0 = rlo + 64 * tl;
;                 f32x4 sc[4];
; #pragma unroll
;                 for (int jt = 0; jt < 4; ++jt) {
;                     const int row = 16 * jt + fr; const int sw = (row >> 1) & 7;
;                     const bf16x8 k0 = *(const LAS bf16x8*)(lds + AT_K + buf * 8192 + row * 128 + ((fq ^ sw) << 4));
;                     const bf16x8 k1 = *(const LAS bf16x8*)(lds + AT_K + buf * 8192 + row * 128 + (((4 + fq) ^ sw) << 4));
;                     f32x4 acc = (f32x4){0.f, 0.f, 0.f, 0.f}; acc = MFMA16(k0, qf[0], acc); acc = MFMA16(k1, qf[1], acc); sc[jt] = acc;
;                 }
;                 float sv[16]; bool ok[16];
; #pragma unroll
;                 for (int jt = 0; jt < 4; ++jt)
; #pragma unroll
;                     for (int rr = 0; rr < 4; ++rr) {
;                         bool valid = true;
;                         if (SWA && local) { const int dd = tkey0 + 16 * jt + 4 * fq + rr - (tq0 + fr); valid = (dd <= 128) && (dd >= -128); }
;                         sv[jt * 4 + rr] = valid ? sc[jt][rr] : -1e30f; ok[jt * 4 + rr] = valid;
;                     }
;                 float cmax = sv[0];
; #pragma unroll
;                 for (int e = 1; e < 16; ++e) cmax = fmaxf(cmax, sv[e]);
;                 cmax = fmaxf(cmax, shx(cmax, 16, lane)); cmax = fmaxf(cmax, shx(cmax, 32, lane));
;                 const float m_new = fmaxf(m_run, cmax);
;                 const float alpha = __builtin_amdgcn_exp2f((m_run - m_new) * LOG2E);
;                 float p[16], psum = 0.f;
; #pragma unroll
;                 for (int e = 0; e < 16; ++e) { p[e] = ok[e] ? __builtin_amdgcn_exp2f((sv[e] - m_new) * LOG2E) : 0.f; psum += p[e]; }
;                 l_run = l_run * alpha + psum; m_run = m_new;
;                 u32x4 pw0, pw1; pw0.x = pk2(p[0], p[1]); pw0.y = pk2(p[2], p[3]); pw0.z = pk2(p[4], p[5]); pw0.w = pk2(p[6], p[7]);
;                 pw1.x = pk2(p[8], p[9]); pw1.y = pk2(p[10], p[11]); pw1.z = pk2(p[12], p[13]); pw1.w = pk2(p[14], p[15]);
;                 const bf16x8 pf0 = __builtin_bit_cast(bf16x8, pw0), pf1 = __builtin_bit_cast(bf16x8, pw1);
;                 if (__builtin_amdgcn_ballot_w64(alpha != 1.f) != 0ull) {
; #pragma unroll
.LBB0_94:
	ds_read_b128 v[164:167], v79 offset:16384
	ds_read_b128 v[168:171], v80 offset:16384
	ds_read_b128 v[172:175], v79 offset:18432
	ds_read_b128 v[176:179], v80 offset:18432
	ds_read_b128 v[180:183], v79 offset:20480
	ds_read_b128 v[184:187], v80 offset:20480
	ds_read_b128 v[192:195], v79 offset:22528
	ds_read_b128 v[196:199], v80 offset:22528
	s_waitcnt lgkmcnt(6)
	v_mfma_f32_16x16x32_bf16 v[24:27], v[164:167], v[12:15], 0
	v_mfma_f32_16x16x32_bf16 v[24:27], v[168:171], v[16:19], v[24:27]
	s_waitcnt lgkmcnt(4)
	v_mfma_f32_16x16x32_bf16 v[28:31], v[172:175], v[12:15], 0
	s_nop 3
	s_nop 1
	v_max_f32_e32 v60, v25, v25
	s_nop 0
	v_max_f32_e32 v81, v24, v24
	v_max_f32_e32 v60, v81, v60
	v_mfma_f32_16x16x32_bf16 v[28:31], v[176:179], v[16:19], v[28:31]
	v_max3_f32 v60, v60, v26, v27
	s_waitcnt lgkmcnt(2)
	v_mfma_f32_16x16x32_bf16 v[32:35], v[180:183], v[12:15], 0
	s_nop 2
	s_nop 1
	v_max3_f32 v60, v60, v28, v29
	s_nop 0
	v_max3_f32 v60, v60, v30, v31
	v_mfma_f32_16x16x32_bf16 v[32:35], v[184:187], v[16:19], v[32:35]
	s_waitcnt lgkmcnt(0)
	v_mfma_f32_16x16x32_bf16 v[36:39], v[192:195], v[12:15], 0
	s_nop 3
	s_nop 1
	v_max3_f32 v60, v60, v32, v33
	s_nop 0
	v_max3_f32 v60, v60, v34, v35
	v_mfma_f32_16x16x32_bf16 v[36:39], v[196:199], v[16:19], v[36:39]
	s_nop 7
	v_max3_f32 v60, v60, v36, v37
	v_max3_f32 v60, v60, v38, v39
	v_xor_b32_e32 v157, 64, v69
	ds_bpermute_b32 v81, v68, v60
	ds_bpermute_b32 v158, v69, v60
	ds_bpermute_b32 v159, v157, v60
	s_waitcnt lgkmcnt(0)
	v_max3_f32 v60, v60, v81, v158
	v_max3_f32 v82, v85, v60, v159
	v_sub_f32_e32 v60, v85, v82
	v_mul_f32_e32 v60, 0x3fb8aa3b, v60
	v_exp_f32_e32 v60, v60
	s_nop 0
	v_cmp_neq_f32_e32 vcc, 1.0, v60
	s_cbranch_vccz .LBB0_96
	v_pk_mul_f32 v[22:23], v[22:23], v[60:61] op_sel_hi:[1,0]
	v_pk_mul_f32 v[20:21], v[20:21], v[60:61] op_sel_hi:[1,0]
	v_pk_mul_f32 v[10:11], v[10:11], v[60:61] op_sel_hi:[1,0]
	v_pk_mul_f32 v[8:9], v[8:9], v[60:61] op_sel_hi:[1,0]
	v_pk_mul_f32 v[6:7], v[6:7], v[60:61] op_sel_hi:[1,0]
	v_pk_mul_f32 v[4:5], v[4:5], v[60:61] op_sel_hi:[1,0]
	v_pk_mul_f32 v[2:3], v[2:3], v[60:61] op_sel_hi:[1,0]
	v_pk_mul_f32 v[0:1], v[0:1], v[60:61] op_sel_hi:[1,0]

; #define LAS __attribute__((address_space(3)))
; template <bool SWA>
; DI void attn_phase(const Ctx& a, LAS unsigned char* lds) {
;     ...
;             if (nck == 2) {
;                 const int tkey0 = rlo + 64 * tl;
;                 f32x4 sc[4];
; #pragma unroll
;                 for (int jt = 0; jt < 4; ++jt) {
;                     const int row = 16 * jt + fr; const int sw = (row >> 1) & 7;
;                     const bf16x8 k0 = *(const LAS bf16x8*)(lds + AT_K + buf * 8192 + row * 128 + ((fq ^ sw) << 4));
;                     const bf16x8 k1 = *(const LAS bf16x8*)(lds + AT_K + buf * 8192 + row * 128 + (((4 + fq) ^ sw) << 4));
;                     f32x4 acc = (f32x4){0.f, 0.f, 0.f, 0.f}; acc = MFMA16(k0, qf[0], acc); acc = MFMA16(k1, qf[1], acc); sc[jt] = acc;
;                 }
;                 float sv[16]; bool ok[16];
; #pragma unroll
;                 for (int jt = 0; jt < 4; ++jt)
; #pragma unroll
;                     for (int rr = 0; rr < 4; ++rr) {
;                         bool valid = true;
;                         if (SWA && local) { const int dd = tkey0 + 16 * jt + 4 * fq + rr - (tq0 + fr); valid = (dd <= 128) && (dd >= -128); }
;                         sv[jt * 4 + rr] = valid ? sc[jt][rr] : -1e30f; ok[jt * 4 + rr] = valid;
;                     }
;                 float cmax = sv[0];
; #pragma unroll
;                 for (int e = 1; e < 16; ++e) cmax = fmaxf(cmax, sv[e]);
;                 cmax = fmaxf(cmax, shx(cmax, 16, lane)); cmax = fmaxf(cmax, shx(cmax, 32, lane));
;                 const float m_new = fmaxf(m_run, cmax);
;                 const float alpha = __builtin_amdgcn_exp2f((m_run - m_new) * LOG2E);
;                 float p[16], psum = 0.f;
; #pragma unroll
;                 for (int e = 0; e < 16; ++e) { p[e] = ok[e] ? __builtin_amdgcn_exp2f((sv[e] - m_new) * LOG2E) : 0.f; psum += p[e]; }
;                 l_run = l_run * alpha + psum; m_run = m_new;
;                 u32x4 pw0, pw1; pw0.x = pk2(p[0], p[1]); pw0.y = pk2(p[2], p[3]); pw0.z = pk2(p[4], p[5]); pw0.w = pk2(p[6], p[7]);
;                 pw1.x = pk2(p[8], p[9]); pw1.y = pk2(p[10], p[11]); pw1.z = pk2(p[12], p[13]); pw1.w = pk2(p[14], p[15]);
;                 const bf16x8 pf0 = __builtin_bit_cast(bf16x8, pw0), pf1 = __builtin_bit_cast(bf16x8, pw1);
;                 if (__builtin_amdgcn_ballot_w64(alpha != 1.f) != 0ull) {
; #pragma unroll
.LBB0_103:
	ds_read_b128 v[164:167], v79
	ds_read_b128 v[168:171], v80
	ds_read_b128 v[172:175], v79 offset:2048
	ds_read_b128 v[176:179], v80 offset:2048
	ds_read_b128 v[180:183], v79 offset:4096
	ds_read_b128 v[184:187], v80 offset:4096
	ds_read_b128 v[192:195], v79 offset:6144
	ds_read_b128 v[196:199], v80 offset:6144
	s_waitcnt lgkmcnt(6)
	v_mfma_f32_16x16x32_bf16 v[24:27], v[164:167], v[12:15], 0
	v_mfma_f32_16x16x32_bf16 v[24:27], v[168:171], v[16:19], v[24:27]
	s_waitcnt lgkmcnt(4)
	v_mfma_f32_16x16x32_bf16 v[28:31], v[172:175], v[12:15], 0
	s_nop 3
	s_nop 1
	v_max_f32_e32 v60, v25, v25
	v_mfma_f32_16x16x32_bf16 v[28:31], v[176:179], v[16:19], v[28:31]
	s_waitcnt lgkmcnt(2)
	v_mfma_f32_16x16x32_bf16 v[32:35], v[180:183], v[12:15], 0
	v_mfma_f32_16x16x32_bf16 v[32:35], v[184:187], v[16:19], v[32:35]
	v_max_f32_e32 v79, v24, v24
	v_max_f32_e32 v60, v79, v60
	s_waitcnt lgkmcnt(0)
	v_mfma_f32_16x16x32_bf16 v[36:39], v[192:195], v[12:15], 0
	v_max3_f32 v60, v60, v26, v27
	v_max3_f32 v60, v60, v28, v29
	v_max3_f32 v60, v60, v30, v31
	v_mfma_f32_16x16x32_bf16 v[36:39], v[196:199], v[16:19], v[36:39]
	v_max3_f32 v60, v60, v32, v33
	v_max3_f32 v60, v60, v34, v35
	s_nop 5
	v_max3_f32 v60, v60, v36, v37
	v_max3_f32 v60, v60, v38, v39
	v_xor_b32_e32 v157, 64, v69
	ds_bpermute_b32 v79, v68, v60
	ds_bpermute_b32 v158, v69, v60
	ds_bpermute_b32 v159, v157, v60
	s_waitcnt lgkmcnt(0)
	v_max3_f32 v60, v60, v79, v158
	v_max3_f32 v79, v82, v60, v159
	v_sub_f32_e32 v60, v82, v79
	v_mul_f32_e32 v60, 0x3fb8aa3b, v60
	v_exp_f32_e32 v60, v60
	s_nop 0
	v_cmp_neq_f32_e32 vcc, 1.0, v60
	s_cbranch_vccz .LBB0_105
	v_pk_mul_f32 v[22:23], v[22:23], v[60:61] op_sel_hi:[1,0]
	v_pk_mul_f32 v[20:21], v[20:21], v[60:61] op_sel_hi:[1,0]
	v_pk_mul_f32 v[10:11], v[10:11], v[60:61] op_sel_hi:[1,0]
	v_pk_mul_f32 v[8:9], v[8:9], v[60:61] op_sel_hi:[1,0]
	v_pk_mul_f32 v[6:7], v[6:7], v[60:61] op_sel_hi:[1,0]
	v_pk_mul_f32 v[4:5], v[4:5], v[60:61] op_sel_hi:[1,0]
	v_pk_mul_f32 v[2:3], v[2:3], v[60:61] op_sel_hi:[1,0]
	v_pk_mul_f32 v[0:1], v[0:1], v[60:61] op_sel_hi:[1,0]

; #define LAS __attribute__((address_space(3)))
; template <bool SWA>
; DI void attn_phase(const Ctx& a, LAS unsigned char* lds) {
;     ...
;             if (nck == 2) {
;                 const int tkey0 = rlo + 64 * tl;
;                 f32x4 sc[4];
; #pragma unroll
;                 for (int jt = 0; jt < 4; ++jt) {
;                     const int row = 16 * jt + fr; const int sw = (row >> 1) & 7;
;                     const bf16x8 k0 = *(const LAS bf16x8*)(lds + AT_K + buf * 8192 + row * 128 + ((fq ^ sw) << 4));
;                     const bf16x8 k1 = *(const LAS bf16x8*)(lds + AT_K + buf * 8192 + row * 128 + (((4 + fq) ^ sw) << 4));
;                     f32x4 acc = (f32x4){0.f, 0.f, 0.f, 0.f}; acc = MFMA16(k0, qf[0], acc); acc = MFMA16(k1, qf[1], acc); sc[jt] = acc;
;                 }
;                 float sv[16]; bool ok[16];
; #pragma unroll
;                 for (int jt = 0; jt < 4; ++jt)
; #pragma unroll
;                     for (int rr = 0; rr < 4; ++rr) {
;                         bool valid = true;
;                         if (SWA && local) { const int dd = tkey0 + 16 * jt + 4 * fq + rr - (tq0 + fr); valid = (dd <= 128) && (dd >= -128); }
;                         sv[jt * 4 + rr] = valid ? sc[jt][rr] : -1e30f; ok[jt * 4 + rr] = valid;
;                     }
;                 float cmax = sv[0];
; #pragma unroll
;                 for (int e = 1; e < 16; ++e) cmax = fmaxf(cmax, sv[e]);
;                 cmax = fmaxf(cmax, shx(cmax, 16, lane)); cmax = fmaxf(cmax, shx(cmax, 32, lane));
;                 const float m_new = fmaxf(m_run, cmax);
;                 const float alpha = __builtin_amdgcn_exp2f((m_run - m_new) * LOG2E);
;                 float p[16], psum = 0.f;
; #pragma unroll
;                 for (int e = 0; e < 16; ++e) { p[e] = ok[e] ? __builtin_amdgcn_exp2f((sv[e] - m_new) * LOG2E) : 0.f; psum += p[e]; }
;                 l_run = l_run * alpha + psum; m_run = m_new;
;                 u32x4 pw0, pw1; pw0.x = pk2(p[0], p[1]); pw0.y = pk2(p[2], p[3]); pw0.z = pk2(p[4], p[5]); pw0.w = pk2(p[6], p[7]);
;                 pw1.x = pk2(p[8], p[9]); pw1.y = pk2(p[10], p[11]); pw1.z = pk2(p[12], p[13]); pw1.w = pk2(p[14], p[15]);
;                 const bf16x8 pf0 = __builtin_bit_cast(bf16x8, pw0), pf1 = __builtin_bit_cast(bf16x8, pw1);
;                 if (__builtin_amdgcn_ballot_w64(alpha != 1.f) != 0ull) {
; #pragma unroll
.LBB0_113:
	s_lshl_b32 s79, s78, 13
	v_add_u32_e32 v24, s79, v65
	v_add_u32_e32 v38, v24, v66
	v_add_u32_e32 v24, v24, v67
	ds_read_b128 v[116:119], v38
	ds_read_b128 v[120:123], v24
	ds_read_b128 v[124:127], v38 offset:2048
	ds_read_b128 v[128:131], v24 offset:2048
	ds_read_b128 v[132:135], v38 offset:4096
	ds_read_b128 v[136:139], v24 offset:4096
	ds_read_b128 v[84:87], v38 offset:6144
	ds_read_b128 v[88:91], v24 offset:6144
	s_movk_i32 s20, 0x101
	s_waitcnt lgkmcnt(6)
	v_mfma_f32_16x16x32_bf16 v[28:31], v[116:119], v[12:15], 0
	v_mfma_f32_16x16x32_bf16 v[30:33], v[120:123], v[16:19], v[28:31]
	s_waitcnt lgkmcnt(4)
	v_mfma_f32_16x16x32_bf16 v[34:37], v[124:127], v[12:15], 0
	v_mfma_f32_16x16x32_bf16 v[34:37], v[128:131], v[16:19], v[34:37]
	s_waitcnt lgkmcnt(2)
	v_mfma_f32_16x16x32_bf16 v[80:83], v[132:135], v[12:15], 0
	v_mfma_f32_16x16x32_bf16 v[80:83], v[136:139], v[16:19], v[80:83]
	v_add_u32_e32 v24, s75, v26
	v_add_u32_e32 v28, 0x80, v24
	v_cmp_gt_u32_e64 s[66:67], s20, v28
	v_add_u32_e32 v28, 0x81, v24
	v_cmp_gt_u32_e64 s[70:71], s20, v28
	v_add_u32_e32 v28, 0x82, v24
	v_cmp_gt_u32_e64 s[68:69], s20, v28
	v_add_u32_e32 v28, 0x83, v24
	v_cmp_gt_u32_e64 s[64:65], s20, v28
	v_add_u32_e32 v28, 0x90, v24
	v_cmp_gt_u32_e64 s[62:63], s20, v28
	v_add_u32_e32 v28, 0x91, v24
	v_cmp_gt_u32_e64 s[60:61], s20, v28
	v_add_u32_e32 v28, 0x92, v24
	v_cmp_gt_u32_e64 s[58:59], s20, v28
	v_add_u32_e32 v28, 0x93, v24
	v_cmp_gt_u32_e64 s[56:57], s20, v28
	v_add_u32_e32 v28, 0xa0, v24
	v_cmp_gt_u32_e64 s[54:55], s20, v28
	v_add_u32_e32 v28, 0xa1, v24
	v_cmp_gt_u32_e64 s[52:53], s20, v28
	v_add_u32_e32 v28, 0xa2, v24
	v_cmp_gt_u32_e64 s[50:51], s20, v28
	v_add_u32_e32 v28, 0xa3, v24
	v_cmp_gt_u32_e64 s[48:49], s20, v28
	v_add_u32_e32 v28, 0xb0, v24
	s_waitcnt lgkmcnt(0)
	v_mfma_f32_16x16x32_bf16 v[84:87], v[84:87], v[12:15], 0
	v_cmp_gt_u32_e64 s[46:47], s20, v28
	v_add_u32_e32 v28, 0xb1, v24
	v_cndmask_b32_e64 v29, v202, v30, s[66:67]
	v_cndmask_b32_e64 v30, v202, v31, s[70:71]
	v_cmp_gt_u32_e64 s[44:45], s20, v28
	v_add_u32_e32 v28, 0xb2, v24
	v_add_u32_e32 v24, 0xb3, v24
	v_cmp_gt_u32_e64 s[42:43], s20, v28
	v_cmp_gt_u32_e64 s[40:41], s20, v24
	v_max_f32_e32 v24, v30, v30
	v_max_f32_e32 v28, v29, v29
	v_cndmask_b32_e64 v31, v202, v32, s[68:69]
	v_cndmask_b32_e64 v32, v202, v33, s[64:65]
	v_max_f32_e32 v24, v28, v24
	v_mfma_f32_16x16x32_bf16 v[84:87], v[88:91], v[16:19], v[84:87]
	v_cndmask_b32_e64 v33, v202, v34, s[62:63]
	v_cndmask_b32_e64 v34, v202, v35, s[60:61]
	v_max3_f32 v24, v24, v31, v32
	v_cndmask_b32_e64 v35, v202, v36, s[58:59]
	v_cndmask_b32_e64 v36, v202, v37, s[56:57]
	v_max3_f32 v24, v24, v33, v34
	v_cndmask_b32_e64 v37, v202, v80, s[54:55]
	v_cndmask_b32_e64 v38, v202, v81, s[52:53]
	v_max3_f32 v24, v24, v35, v36
	v_cndmask_b32_e64 v39, v202, v82, s[50:51]
	v_cndmask_b32_e64 v49, v202, v83, s[48:49]
	v_max3_f32 v24, v24, v37, v38
	v_cndmask_b32_e64 v51, v202, v84, s[46:47]
	v_cndmask_b32_e64 v55, v202, v85, s[44:45]
	v_max3_f32 v24, v24, v39, v49
	v_cndmask_b32_e64 v60, v202, v86, s[42:43]
	v_cndmask_b32_e64 v76, v202, v87, s[40:41]
	v_max3_f32 v24, v24, v51, v55
	v_max3_f32 v24, v24, v60, v76
	v_xor_b32_e32 v157, 64, v69
	ds_bpermute_b32 v28, v68, v24
	ds_bpermute_b32 v158, v69, v24
	ds_bpermute_b32 v159, v157, v24
	s_waitcnt lgkmcnt(0)
	v_max3_f32 v24, v24, v28, v158
	v_max3_f32 v28, v79, v24, v159
	v_sub_f32_e32 v24, v79, v28
	v_mul_f32_e32 v24, 0x3fb8aa3b, v24
	v_exp_f32_e32 v24, v24
	s_nop 0
	v_cmp_neq_f32_e32 vcc, 1.0, v24
	s_cbranch_vccz .LBB0_115
	v_pk_mul_f32 v[6:7], v[6:7], v[24:25] op_sel_hi:[1,0]
	v_pk_mul_f32 v[4:5], v[4:5], v[24:25] op_sel_hi:[1,0]
	v_pk_mul_f32 v[10:11], v[10:11], v[24:25] op_sel_hi:[1,0]
	v_pk_mul_f32 v[8:9], v[8:9], v[24:25] op_sel_hi:[1,0]
	v_pk_mul_f32 v[22:23], v[22:23], v[24:25] op_sel_hi:[1,0]
	v_pk_mul_f32 v[20:21], v[20:21], v[24:25] op_sel_hi:[1,0]
	v_pk_mul_f32 v[2:3], v[2:3], v[24:25] op_sel_hi:[1,0]
	v_pk_mul_f32 v[0:1], v[0:1], v[24:25] op_sel_hi:[1,0]

; #define LAS __attribute__((address_space(3)))
; template <bool SWA>
; DI void attn_phase(const Ctx& a, LAS unsigned char* lds) {
;     ...
;             if (nck == 2) {
;                 const int tkey0 = rlo + 64 * tl;
;                 f32x4 sc[4];
; #pragma unroll
;                 for (int jt = 0; jt < 4; ++jt) {
;                     const int row = 16 * jt + fr; const int sw = (row >> 1) & 7;
;                     const bf16x8 k0 = *(const LAS bf16x8*)(lds + AT_K + buf * 8192 + row * 128 + ((fq ^ sw) << 4));
;                     const bf16x8 k1 = *(const LAS bf16x8*)(lds + AT_K + buf * 8192 + row * 128 + (((4 + fq) ^ sw) << 4));
;                     f32x4 acc = (f32x4){0.f, 0.f, 0.f, 0.f}; acc = MFMA16(k0, qf[0], acc); acc = MFMA16(k1, qf[1], acc); sc[jt] = acc;
;                 }
;                 float sv[16]; bool ok[16];
; #pragma unroll
;                 for (int jt = 0; jt < 4; ++jt)
; #pragma unroll
;                     for (int rr = 0; rr < 4; ++rr) {
;                         bool valid = true;
;                         if (SWA && local) { const int dd = tkey0 + 16 * jt + 4 * fq + rr - (tq0 + fr); valid = (dd <= 128) && (dd >= -128); }
;                         sv[jt * 4 + rr] = valid ? sc[jt][rr] : -1e30f; ok[jt * 4 + rr] = valid;
;                     }
;                 float cmax = sv[0];
; #pragma unroll
;                 for (int e = 1; e < 16; ++e) cmax = fmaxf(cmax, sv[e]);
;                 cmax = fmaxf(cmax, shx(cmax, 16, lane)); cmax = fmaxf(cmax, shx(cmax, 32, lane));
;                 const float m_new = fmaxf(m_run, cmax);
;                 const float alpha = __builtin_amdgcn_exp2f((m_run - m_new) * LOG2E);
;                 float p[16], psum = 0.f;
; #pragma unroll
;                 for (int e = 0; e < 16; ++e) { p[e] = ok[e] ? __builtin_amdgcn_exp2f((sv[e] - m_new) * LOG2E) : 0.f; psum += p[e]; }
;                 l_run = l_run * alpha + psum; m_run = m_new;
;                 u32x4 pw0, pw1; pw0.x = pk2(p[0], p[1]); pw0.y = pk2(p[2], p[3]); pw0.z = pk2(p[4], p[5]); pw0.w = pk2(p[6], p[7]);
;                 pw1.x = pk2(p[8], p[9]); pw1.y = pk2(p[10], p[11]); pw1.z = pk2(p[12], p[13]); pw1.w = pk2(p[14], p[15]);
;                 const bf16x8 pf0 = __builtin_bit_cast(bf16x8, pw0), pf1 = __builtin_bit_cast(bf16x8, pw1);
;                 if (__builtin_amdgcn_ballot_w64(alpha != 1.f) != 0ull) {
; #pragma unroll
.LBB0_151:
	ds_read_b128 v[164:167], v75 offset:8192
	ds_read_b128 v[168:171], v76 offset:8192
	ds_read_b128 v[172:175], v75 offset:10240
	ds_read_b128 v[176:179], v76 offset:10240
	ds_read_b128 v[180:183], v75 offset:12288
	ds_read_b128 v[184:187], v76 offset:12288
	ds_read_b128 v[192:195], v75 offset:14336
	ds_read_b128 v[196:199], v76 offset:14336
	s_waitcnt lgkmcnt(6)
	v_mfma_f32_16x16x32_bf16 v[24:27], v[164:167], v[0:3], 0
	v_mfma_f32_16x16x32_bf16 v[24:27], v[168:171], v[4:7], v[24:27]
	s_waitcnt lgkmcnt(4)
	v_mfma_f32_16x16x32_bf16 v[28:31], v[172:175], v[0:3], 0
	v_mfma_f32_16x16x32_bf16 v[28:31], v[176:179], v[4:7], v[28:31]
	s_waitcnt lgkmcnt(2)
	v_mfma_f32_16x16x32_bf16 v[32:35], v[180:183], v[0:3], 0
	v_mfma_f32_16x16x32_bf16 v[32:35], v[184:187], v[4:7], v[32:35]
	s_waitcnt lgkmcnt(0)
	v_mfma_f32_16x16x32_bf16 v[36:39], v[192:195], v[0:3], 0
	v_mfma_f32_16x16x32_bf16 v[36:39], v[196:199], v[4:7], v[36:39]
	v_max_f32_e32 v86, v25, v25
	v_max_f32_e32 v87, v24, v24
	v_max_f32_e32 v86, v87, v86
	v_max3_f32 v86, v86, v26, v27
	v_max3_f32 v86, v86, v28, v29
	v_max3_f32 v86, v86, v30, v31
	v_max3_f32 v86, v86, v32, v33
	v_max3_f32 v86, v86, v34, v35
	v_max3_f32 v86, v86, v36, v37
	v_max3_f32 v86, v86, v38, v39
	v_xor_b32_e32 v157, 64, v70
	ds_bpermute_b32 v87, v69, v86
	ds_bpermute_b32 v158, v70, v86
	ds_bpermute_b32 v159, v157, v86
	s_waitcnt lgkmcnt(0)
	v_max3_f32 v86, v86, v87, v158
	v_max3_f32 v87, v58, v86, v159
	v_sub_f32_e32 v58, v58, v87
	v_mul_f32_e32 v58, 0x3fb8aa3b, v58
	v_exp_f32_e32 v58, v58
	s_nop 0
	v_cmp_neq_f32_e32 vcc, 1.0, v58
	s_cbranch_vccz .LBB0_153
	v_pk_mul_f32 v[10:11], v[10:11], v[58:59] op_sel_hi:[1,0]
	v_pk_mul_f32 v[8:9], v[8:9], v[58:59] op_sel_hi:[1,0]
	v_pk_mul_f32 v[22:23], v[22:23], v[58:59] op_sel_hi:[1,0]
	v_pk_mul_f32 v[20:21], v[20:21], v[58:59] op_sel_hi:[1,0]
	v_pk_mul_f32 v[18:19], v[18:19], v[58:59] op_sel_hi:[1,0]
	v_pk_mul_f32 v[16:17], v[16:17], v[58:59] op_sel_hi:[1,0]
	v_pk_mul_f32 v[14:15], v[14:15], v[58:59] op_sel_hi:[1,0]
	v_pk_mul_f32 v[12:13], v[12:13], v[58:59] op_sel_hi:[1,0]

; #define LAS __attribute__((address_space(3)))
; template <bool SWA>
; DI void attn_phase(const Ctx& a, LAS unsigned char* lds) {
;     ...
;             if (nck == 2) {
;                 const int tkey0 = rlo + 64 * tl;
;                 f32x4 sc[4];
; #pragma unroll
;                 for (int jt = 0; jt < 4; ++jt) {
;                     const int row = 16 * jt + fr; const int sw = (row >> 1) & 7;
;                     const bf16x8 k0 = *(const LAS bf16x8*)(lds + AT_K + buf * 8192 + row * 128 + ((fq ^ sw) << 4));
;                     const bf16x8 k1 = *(const LAS bf16x8*)(lds + AT_K + buf * 8192 + row * 128 + (((4 + fq) ^ sw) << 4));
;                     f32x4 acc = (f32x4){0.f, 0.f, 0.f, 0.f}; acc = MFMA16(k0, qf[0], acc); acc = MFMA16(k1, qf[1], acc); sc[jt] = acc;
;                 }
;                 float sv[16]; bool ok[16];
; #pragma unroll
;                 for (int jt = 0; jt < 4; ++jt)
; #pragma unroll
;                     for (int rr = 0; rr < 4; ++rr) {
;                         bool valid = true;
;                         if (SWA && local) { const int dd = tkey0 + 16 * jt + 4 * fq + rr - (tq0 + fr); valid = (dd <= 128) && (dd >= -128); }
;                         sv[jt * 4 + rr] = valid ? sc[jt][rr] : -1e30f; ok[jt * 4 + rr] = valid;
;                     }
;                 float cmax = sv[0];
; #pragma unroll
;                 for (int e = 1; e < 16; ++e) cmax = fmaxf(cmax, sv[e]);
;                 cmax = fmaxf(cmax, shx(cmax, 16, lane)); cmax = fmaxf(cmax, shx(cmax, 32, lane));
;                 const float m_new = fmaxf(m_run, cmax);
;                 const float alpha = __builtin_amdgcn_exp2f((m_run - m_new) * LOG2E);
;                 float p[16], psum = 0.f;
; #pragma unroll
;                 for (int e = 0; e < 16; ++e) { p[e] = ok[e] ? __builtin_amdgcn_exp2f((sv[e] - m_new) * LOG2E) : 0.f; psum += p[e]; }
;                 l_run = l_run * alpha + psum; m_run = m_new;
;                 u32x4 pw0, pw1; pw0.x = pk2(p[0], p[1]); pw0.y = pk2(p[2], p[3]); pw0.z = pk2(p[4], p[5]); pw0.w = pk2(p[6], p[7]);
;                 pw1.x = pk2(p[8], p[9]); pw1.y = pk2(p[10], p[11]); pw1.z = pk2(p[12], p[13]); pw1.w = pk2(p[14], p[15]);
;                 const bf16x8 pf0 = __builtin_bit_cast(bf16x8, pw0), pf1 = __builtin_bit_cast(bf16x8, pw1);
;                 if (__builtin_amdgcn_ballot_w64(alpha != 1.f) != 0ull) {
; #pragma unroll
.LBB0_160:
	ds_read_b128 v[164:167], v75 offset:16384
	ds_read_b128 v[168:171], v76 offset:16384
	ds_read_b128 v[172:175], v75 offset:18432
	ds_read_b128 v[176:179], v76 offset:18432
	ds_read_b128 v[180:183], v75 offset:20480
	ds_read_b128 v[184:187], v76 offset:20480
	ds_read_b128 v[192:195], v75 offset:22528
	ds_read_b128 v[196:199], v76 offset:22528
	s_waitcnt lgkmcnt(6)
	v_mfma_f32_16x16x32_bf16 v[24:27], v[164:167], v[0:3], 0
	v_mfma_f32_16x16x32_bf16 v[24:27], v[168:171], v[4:7], v[24:27]
	s_waitcnt lgkmcnt(4)
	v_mfma_f32_16x16x32_bf16 v[28:31], v[172:175], v[0:3], 0
	s_nop 3
	s_nop 1
	v_max_f32_e32 v49, v25, v25
	s_nop 0
	v_max_f32_e32 v58, v24, v24
	v_max_f32_e32 v49, v58, v49
	v_mfma_f32_16x16x32_bf16 v[28:31], v[176:179], v[4:7], v[28:31]
	v_max3_f32 v49, v49, v26, v27
	s_waitcnt lgkmcnt(2)
	v_mfma_f32_16x16x32_bf16 v[32:35], v[180:183], v[0:3], 0
	s_nop 2
	s_nop 1
	v_max3_f32 v49, v49, v28, v29
	s_nop 0
	v_max3_f32 v49, v49, v30, v31
	v_mfma_f32_16x16x32_bf16 v[32:35], v[184:187], v[4:7], v[32:35]
	s_waitcnt lgkmcnt(0)
	v_mfma_f32_16x16x32_bf16 v[36:39], v[192:195], v[0:3], 0
	s_nop 3
	s_nop 1
	v_max3_f32 v49, v49, v32, v33
	s_nop 0
	v_max3_f32 v49, v49, v34, v35
	v_mfma_f32_16x16x32_bf16 v[36:39], v[196:199], v[4:7], v[36:39]
	s_nop 7
	v_max3_f32 v49, v49, v36, v37
	v_max3_f32 v49, v49, v38, v39
	v_xor_b32_e32 v157, 64, v70
	ds_bpermute_b32 v58, v69, v49
	ds_bpermute_b32 v158, v70, v49
	ds_bpermute_b32 v159, v157, v49
	s_waitcnt lgkmcnt(0)
	v_max3_f32 v49, v49, v58, v158
	v_max3_f32 v85, v87, v49, v159
	v_sub_f32_e32 v49, v87, v85
	v_mul_f32_e32 v49, 0x3fb8aa3b, v49
	v_exp_f32_e32 v58, v49
	s_nop 0
	v_cmp_neq_f32_e32 vcc, 1.0, v58
	s_cbranch_vccz .LBB0_162
	v_pk_mul_f32 v[14:15], v[14:15], v[58:59] op_sel_hi:[1,0]
	v_pk_mul_f32 v[12:13], v[12:13], v[58:59] op_sel_hi:[1,0]
	v_pk_mul_f32 v[18:19], v[18:19], v[58:59] op_sel_hi:[1,0]
	v_pk_mul_f32 v[16:17], v[16:17], v[58:59] op_sel_hi:[1,0]
	v_pk_mul_f32 v[22:23], v[22:23], v[58:59] op_sel_hi:[1,0]
	v_pk_mul_f32 v[20:21], v[20:21], v[58:59] op_sel_hi:[1,0]
	v_pk_mul_f32 v[10:11], v[10:11], v[58:59] op_sel_hi:[1,0]
	v_pk_mul_f32 v[8:9], v[8:9], v[58:59] op_sel_hi:[1,0]

; #define LAS __attribute__((address_space(3)))
; template <bool SWA>
; DI void attn_phase(const Ctx& a, LAS unsigned char* lds) {
;     ...
;             if (nck == 2) {
;                 const int tkey0 = rlo + 64 * tl;
;                 f32x4 sc[4];
; #pragma unroll
;                 for (int jt = 0; jt < 4; ++jt) {
;                     const int row = 16 * jt + fr; const int sw = (row >> 1) & 7;
;                     const bf16x8 k0 = *(const LAS bf16x8*)(lds + AT_K + buf * 8192 + row * 128 + ((fq ^ sw) << 4));
;                     const bf16x8 k1 = *(const LAS bf16x8*)(lds + AT_K + buf * 8192 + row * 128 + (((4 + fq) ^ sw) << 4));
;                     f32x4 acc = (f32x4){0.f, 0.f, 0.f, 0.f}; acc = MFMA16(k0, qf[0], acc); acc = MFMA16(k1, qf[1], acc); sc[jt] = acc;
;                 }
;                 float sv[16]; bool ok[16];
; #pragma unroll
;                 for (int jt = 0; jt < 4; ++jt)
; #pragma unroll
;                     for (int rr = 0; rr < 4; ++rr) {
;                         bool valid = true;
;                         if (SWA && local) { const int dd = tkey0 + 16 * jt + 4 * fq + rr - (tq0 + fr); valid = (dd <= 128) && (dd >= -128); }
;                         sv[jt * 4 + rr] = valid ? sc[jt][rr] : -1e30f; ok[jt * 4 + rr] = valid;
;                     }
;                 float cmax = sv[0];
; #pragma unroll
;                 for (int e = 1; e < 16; ++e) cmax = fmaxf(cmax, sv[e]);
;                 cmax = fmaxf(cmax, shx(cmax, 16, lane)); cmax = fmaxf(cmax, shx(cmax, 32, lane));
;                 const float m_new = fmaxf(m_run, cmax);
;                 const float alpha = __builtin_amdgcn_exp2f((m_run - m_new) * LOG2E);
;                 float p[16], psum = 0.f;
; #pragma unroll
;                 for (int e = 0; e < 16; ++e) { p[e] = ok[e] ? __builtin_amdgcn_exp2f((sv[e] - m_new) * LOG2E) : 0.f; psum += p[e]; }
;                 l_run = l_run * alpha + psum; m_run = m_new;
;                 u32x4 pw0, pw1; pw0.x = pk2(p[0], p[1]); pw0.y = pk2(p[2], p[3]); pw0.z = pk2(p[4], p[5]); pw0.w = pk2(p[6], p[7]);
;                 pw1.x = pk2(p[8], p[9]); pw1.y = pk2(p[10], p[11]); pw1.z = pk2(p[12], p[13]); pw1.w = pk2(p[14], p[15]);
;                 const bf16x8 pf0 = __builtin_bit_cast(bf16x8, pw0), pf1 = __builtin_bit_cast(bf16x8, pw1);
;                 if (__builtin_amdgcn_ballot_w64(alpha != 1.f) != 0ull) {
; #pragma unroll
.LBB0_169:
	ds_read_b128 v[164:167], v75
	ds_read_b128 v[168:171], v76
	ds_read_b128 v[172:175], v75 offset:2048
	ds_read_b128 v[176:179], v76 offset:2048
	ds_read_b128 v[180:183], v75 offset:4096
	ds_read_b128 v[184:187], v76 offset:4096
	ds_read_b128 v[192:195], v75 offset:6144
	ds_read_b128 v[196:199], v76 offset:6144
	s_waitcnt lgkmcnt(6)
	v_mfma_f32_16x16x32_bf16 v[24:27], v[164:167], v[0:3], 0
	v_mfma_f32_16x16x32_bf16 v[24:27], v[168:171], v[4:7], v[24:27]
	s_waitcnt lgkmcnt(4)
	v_mfma_f32_16x16x32_bf16 v[28:31], v[172:175], v[0:3], 0
	s_nop 3
	s_nop 1
	v_max_f32_e32 v49, v25, v25
	s_nop 0
	v_max_f32_e32 v58, v24, v24
	v_max_f32_e32 v49, v58, v49
	v_mfma_f32_16x16x32_bf16 v[28:31], v[176:179], v[4:7], v[28:31]
	v_max3_f32 v49, v49, v26, v27
	s_waitcnt lgkmcnt(2)
	v_mfma_f32_16x16x32_bf16 v[32:35], v[180:183], v[0:3], 0
	s_nop 2
	s_nop 1
	v_max3_f32 v49, v49, v28, v29
	s_nop 0
	v_max3_f32 v49, v49, v30, v31
	v_mfma_f32_16x16x32_bf16 v[32:35], v[184:187], v[4:7], v[32:35]
	s_waitcnt lgkmcnt(0)
	v_mfma_f32_16x16x32_bf16 v[36:39], v[192:195], v[0:3], 0
	s_nop 3
	s_nop 1
	v_max3_f32 v49, v49, v32, v33
	s_nop 0
	v_max3_f32 v49, v49, v34, v35
	v_mfma_f32_16x16x32_bf16 v[36:39], v[196:199], v[4:7], v[36:39]
	s_nop 7
	v_max3_f32 v49, v49, v36, v37
	v_max3_f32 v49, v49, v38, v39
	v_xor_b32_e32 v157, 64, v70
	ds_bpermute_b32 v58, v69, v49
	ds_bpermute_b32 v158, v70, v49
	ds_bpermute_b32 v159, v157, v49
	s_waitcnt lgkmcnt(0)
	v_max3_f32 v49, v49, v58, v158
	v_max3_f32 v49, v85, v49, v159
	v_sub_f32_e32 v58, v85, v49
	v_mul_f32_e32 v58, 0x3fb8aa3b, v58
	v_exp_f32_e32 v58, v58
	s_nop 0
	v_cmp_neq_f32_e32 vcc, 1.0, v58
	s_cbranch_vccz .LBB0_171
	v_pk_mul_f32 v[14:15], v[14:15], v[58:59] op_sel_hi:[1,0]
	v_pk_mul_f32 v[12:13], v[12:13], v[58:59] op_sel_hi:[1,0]
	v_pk_mul_f32 v[18:19], v[18:19], v[58:59] op_sel_hi:[1,0]
	v_pk_mul_f32 v[16:17], v[16:17], v[58:59] op_sel_hi:[1,0]
	v_pk_mul_f32 v[22:23], v[22:23], v[58:59] op_sel_hi:[1,0]
	v_pk_mul_f32 v[20:21], v[20:21], v[58:59] op_sel_hi:[1,0]
	v_pk_mul_f32 v[10:11], v[10:11], v[58:59] op_sel_hi:[1,0]
	v_pk_mul_f32 v[8:9], v[8:9], v[58:59] op_sel_hi:[1,0]

; #define LAS __attribute__((address_space(3)))
; template <bool SWA>
; DI void attn_phase(const Ctx& a, LAS unsigned char* lds) {
;     ...
;             for (int ck = 0; ck < nck; ++ck) {
;                 const int ko = k0off + 32 * ck;
;                 int tkey0 = 0;
;                 if (SWA && local) { tkey0 = rlo + 64 * tl + ko; if (tkey0 + 31 < tq0 - 128 || tkey0 > tq0 + 15 + 128) continue; }
;                 f32x4 sc[2];
; #pragma unroll
;                 for (int jt = 0; jt < 2; ++jt) {
;                     const int row = ko + 16 * jt + fr; const int sw = (row >> 1) & 7;
;                     const bf16x8 k0 = *(const LAS bf16x8*)(lds + AT_K + buf * 8192 + row * 128 + ((fq ^ sw) << 4));
;                     const bf16x8 k1 = *(const LAS bf16x8*)(lds + AT_K + buf * 8192 + row * 128 + (((4 + fq) ^ sw) << 4));
;                     f32x4 acc = (f32x4){0.f, 0.f, 0.f, 0.f}; acc = MFMA16(k0, qf[0], acc); acc = MFMA16(k1, qf[1], acc); sc[jt] = acc;
;                 }
;                 float sv[8]; bool ok[8];
; #pragma unroll
;                 for (int jt = 0; jt < 2; ++jt)
; #pragma unroll
;                     for (int rr = 0; rr < 4; ++rr) {
;                         const int jj = 16 * jt + 4 * fq + rr; float x = sc[jt][rr]; bool valid = true;
;                         if (local) {
;                             if (!SWA) { x += bias[jt * 4 + rr]; }
;                             else { const int dd = tkey0 + jj - (tq0 + fr); valid = (dd <= 128) && (dd >= -128); }
;                         }
;                         sv[jt * 4 + rr] = valid ? x : -1e30f; ok[jt * 4 + rr] = valid;
;                     }
;                 float cmax = sv[0];
; #pragma unroll
;                 for (int e = 1; e < 8; ++e) cmax = fmaxf(cmax, sv[e]);
;                 cmax = fmaxf(cmax, shx(cmax, 16, lane)); cmax = fmaxf(cmax, shx(cmax, 32, lane));
;                 const float m_new = fmaxf(m_run, cmax);
;                 const float alpha = __builtin_amdgcn_exp2f((m_run - m_new) * LOG2E);
;                 float p[8], psum = 0.f;
; #pragma unroll
;                 for (int e = 0; e < 8; ++e) { p[e] = ok[e] ? __builtin_amdgcn_exp2f((sv[e] - m_new) * LOG2E) : 0.f; psum += p[e]; }
;                 l_run = l_run * alpha + psum; m_run = m_new;
;                 u32x4 pw; pw.x = pk2(p[0], p[1]); pw.y = pk2(p[2], p[3]); pw.z = pk2(p[4], p[5]); pw.w = pk2(p[6], p[7]);
.LBB0_180:
	s_add_i32 s20, s16, s48
	v_cmp_ge_i32_e32 vcc, s20, v51
	v_cmp_le_i32_e64 s[42:43], s20, v25
	s_and_b64 s[20:21], vcc, s[42:43]
	s_and_saveexec_b64 s[42:43], s[20:21]
	s_cbranch_execz .LBB0_185
	s_lshl_b32 s49, s45, 13
	s_waitcnt lgkmcnt(0)
	v_add_u32_e32 v116, s49, v87
	v_add_u32_e32 v117, v116, v81
	v_add_u32_e32 v118, v116, v86
	ds_read_b128 v[120:123], v117
	ds_read_b128 v[124:127], v118
	ds_read_b128 v[128:131], v117 offset:2048
	ds_read_b128 v[132:135], v118 offset:2048
	v_add_u32_e32 v116, s49, v74
	v_add3_u32 v117, v116, v84, v72
	v_add3_u32 v118, v116, v85, v72
	ds_read_b64 v[136:137], v117 offset:24576
	ds_read_b64 v[138:139], v118 offset:24576
	ds_read_b64 v[140:141], v117 offset:26624
	ds_read_b64 v[142:143], v118 offset:26624
	ds_read_b64 v[160:161], v117 offset:28672
	ds_read_b64 v[162:163], v118 offset:28672
	ds_read_b64 v[164:165], v117 offset:30720
	ds_read_b64 v[166:167], v118 offset:30720
	v_add_f32_e32 v106, v39, v94
	v_add_f32_e32 v102, v31, v90
	v_add_f32_e32 v103, v33, v91
	v_add_f32_e32 v104, v35, v92
	v_add_f32_e32 v105, v37, v93
	v_add_f32_e32 v107, v83, v95
	v_add_f32_e32 v24, v27, v24
	v_add_f32_e32 v89, v29, v89
	s_waitcnt lgkmcnt(10)
	v_mfma_f32_16x16x32_bf16 v[90:93], v[120:123], v[0:3], 0
	v_mfma_f32_16x16x32_bf16 v[90:93], v[124:127], v[4:7], v[90:93]
	s_waitcnt lgkmcnt(8)
	v_mfma_f32_16x16x32_bf16 v[94:97], v[128:131], v[0:3], 0
	v_mfma_f32_16x16x32_bf16 v[98:101], v[132:135], v[4:7], v[94:97]
	s_nop 6
	v_add_f32_e32 v97, v24, v90
	v_add_f32_e32 v96, v89, v91
	v_add_f32_e32 v95, v102, v92
	v_add_f32_e32 v94, v103, v93
	v_max_f32_e32 v24, v97, v96
	v_add_f32_e32 v93, v104, v98
	v_add_f32_e32 v92, v105, v99
	v_max3_f32 v24, v24, v95, v94
	v_add_f32_e32 v91, v106, v100
	v_add_f32_e32 v90, v107, v101
	v_max3_f32 v24, v24, v93, v92
	v_max3_f32 v24, v24, v91, v90
	v_xor_b32_e32 v157, 64, v70
	ds_bpermute_b32 v89, v69, v24
	ds_bpermute_b32 v158, v70, v24
	ds_bpermute_b32 v159, v157, v24
	s_waitcnt lgkmcnt(0)
	v_max3_f32 v24, v24, v89, v158
	v_max3_f32 v89, v49, v24, v159
	v_sub_f32_e32 v24, v49, v89
	v_mul_f32_e32 v24, 0x3fb8aa3b, v24
	v_exp_f32_e32 v24, v24
	s_nop 0
	v_cmp_neq_f32_e32 vcc, 1.0, v24
	s_cbranch_vccz .LBB0_183
	v_pk_mul_f32 v[14:15], v[14:15], v[24:25] op_sel_hi:[1,0]
	v_pk_mul_f32 v[12:13], v[12:13], v[24:25] op_sel_hi:[1,0]
	v_pk_mul_f32 v[18:19], v[18:19], v[24:25] op_sel_hi:[1,0]
	v_pk_mul_f32 v[16:17], v[16:17], v[24:25] op_sel_hi:[1,0]
	v_pk_mul_f32 v[22:23], v[22:23], v[24:25] op_sel_hi:[1,0]
	v_pk_mul_f32 v[20:21], v[20:21], v[24:25] op_sel_hi:[1,0]
	v_pk_mul_f32 v[10:11], v[10:11], v[24:25] op_sel_hi:[1,0]
	v_pk_mul_f32 v[8:9], v[8:9], v[24:25] op_sel_hi:[1,0]
